# one static s_setprio 1 for waves 4-7 for the whole attention phase (reset to 0 at phase exit)
# speedup vs baseline: 1.0067x; 1.0067x over previous
; DI int otid() { int t = threadIdx.x; asm volatile("" : "+v"(t)); return t; }
; DI void phase_attn(const Params& p, int layer, char* smem) {
;   unsigned* ctr = (unsigned*)(p.ws + OFF_CTRL) + layer * 8;
;   int qsel = 0;
;   int* s_item = (int*)(smem + A_BIAS + 8192);
;   float* sbias = (float*)(smem + A_BIAS);
;   const bf16_t* big = (const bf16_t*)(p.ws + OFF_BIG);
;   bf16_t* ocat = (bf16_t*)(p.ws + OFF_OCAT);
;   NaInfo na0; na0.r0q = 0; na0.c0 = 0; na0.rq = 0; na0.cq = 0; na0.sb = sbias;
;   for (;;) {
;     const int tid = otid(), lane = tid & 63, wave = tid >> 6, r = lane & 31, h = lane >> 5;
;     __syncthreads();
;     const int xq = (blockIdx.x + qsel) & 7;
;     if (tid == 0) *s_item = (int)atomicAdd(ctr + xq, 1u);
;     __syncthreads();
;     const int it = *s_item;
;     if (it >= N_ITEMS_XCD) { if (++qsel >= 8) break; continue; }
.LBB0_104:
	s_andn2_b64 vcc, exec, s[0:1]
	s_cbranch_vccnz .LBB0_407
	s_and_b32 s0, s46, -8
	s_ashr_i32 s1, s0, 31
	s_lshl_b64 s[0:1], s[0:1], 2
	s_add_u32 s0, s86, s0
	s_addc_u32 s1, s87, s1
	v_writelane_b32 v255, s0, 4
	s_nop 1
	v_writelane_b32 v255, s1, 5
	s_nop 0
	v_readlane_b32 s0, v255, 1
	s_mov_b32 s2, s0
	s_mul_i32 s53, s0, 0x744
	s_lshl_b32 s0, s0, 9
	v_readlane_b32 s1, v255, 2
	v_writelane_b32 v255, s0, 6
	s_or_b32 s0, s0, 10
	v_writelane_b32 v255, s0, 7
	s_lshl_b32 s0, s2, 1
	s_lshl_b32 s4, s2, 2
	s_ashr_i32 s1, s0, 31
	s_lshl_b32 s2, s2, 6
	s_ashr_i32 s3, s2, 31
	s_lshl_b64 s[0:1], s[0:1], 2
	s_add_u32 s0, s86, s0
	s_addc_u32 s1, s87, s1
	v_writelane_b32 v255, s0, 8
	s_mov_b32 s56, s53
	s_nop 0
	v_writelane_b32 v255, s1, 9
	s_lshl_b64 s[0:1], s[2:3], 2
	s_waitcnt lgkmcnt(0)
	s_add_u32 s0, s18, s0
	s_addc_u32 s1, s19, s1
	v_writelane_b32 v255, s0, 10
	s_nop 1
	v_writelane_b32 v255, s1, 11
	v_writelane_b32 v255, s4, 12
	s_ashr_i32 s0, s4, 31
	v_writelane_b32 v255, s0, 13
	s_ashr_i32 s1, s53, 31
	s_mov_b32 s0, s53
	v_writelane_b32 v255, s0, 14
	s_nop 1
	v_writelane_b32 v255, s1, 15
	s_mov_b32 s0, 0
	v_writelane_b32 v255, s0, 16
	v_writelane_b32 v255, s53, 17
	v_writelane_b32 v255, s56, 18
	v_readfirstlane_b32 s98, v228
	s_nop 0
	s_cmpk_ge_u32 s98, 0x100
	s_cbranch_scc0 .Lattn_prio_done
	s_setprio 1
.Lattn_prio_done:
	s_branch .LBB0_107
.LBB0_106:
	s_and_b64 vcc, exec, s[0:1]
	s_cbranch_vccnz .LBB0_407

; DI int otid() { int t = threadIdx.x; asm volatile("" : "+v"(t)); return t; }
; DI void phase_attn(const Params& p, int layer, char* smem) {
;     ...
;   for (;;) {
;     const int tid = otid(), lane = tid & 63, wave = tid >> 6, r = lane & 31, h = lane >> 5;
;     __syncthreads();
;     const int xq = (blockIdx.x + qsel) & 7;
;     if (tid == 0) *s_item = (int)atomicAdd(ctr + xq, 1u);
;     __syncthreads();
;     const int it = *s_item;
;     if (it >= N_ITEMS_XCD) { if (++qsel >= 8) break; continue; }
.LBB0_407:
	s_setprio 0
	s_mov_b64 s[0:1], 0
